# phase X items batch-closed too; all 19 barriers after the setup phase are 64-workgroup XCC-local
# speedup vs baseline: 1.0940x; 1.0302x over previous
; __device__ void phase_x(const Params& p, int layer, unsigned char* smem) {
;     ...
;   for (int i = blockIdx.x; i < NA / 2; i += G) {
; #pragma unroll 1
;     for (int h = 0; h < 2; ++h) {
;       int it = h ? (NA - 1 - i) : i;
;       int qt = 31 - (it >> 5); int r = it & 31; int b = r >> 2, hd = r & 3;
;       item_diff(p, layer, b, hd, qt, smem);
;     }
;   }
.LBB0_196:
	s_sub_i32 s12, 0x3ff, s9
	s_cmpk_lg_u32 s8, 0x200
	s_cbranch_scc1 .Ldiffbal_done
	s_lshr_b32 s24, s9, 5
	s_and_b32 s25, s9, 7
	s_lshl_b32 s25, s25, 2
	s_bfe_u32 s29, s9, 0x20003
	s_or_b32 s25, s25, s29
	s_movk_i32 s12, 39
	s_cmpk_lt_u32 s9, 0x100
	s_cselect_b32 s12, 23, s12
	s_sub_i32 s12, s12, s24
	s_lshl_b32 s12, s12, 5
	s_or_b32 s12, s12, s25
	s_lshl_b32 s9, s24, 5
	s_or_b32 s9, s9, s25

; __device__ __forceinline__ int otid() { int t = threadIdx.x; asm volatile("" : "+v"(t)); return t; }
; __device__ void item_compress(const Params& p, int layer, int kv, int b, int g, int ct, unsigned char* smem) {
;   float* sP = (float*)smem;
;   u16* sH = (u16*)(smem + 4 * 16 * 132 * 4);
;   const int tid = otid(), wave = tid >> 6, lane = tid & 63, l15 = lane & 15, quad = lane >> 4;
;   const int c0 = ct * 16;
;   const int c = c0 + l15;
;   const bool cvalid = c < 127;
;   const int col = (kv ? C_VC : C_KC) + g * 64;
;   const float* pe = (kv ? p.pe_v : p.pe_k) + (size_t)layer * 32 * 64;
;   const u16* w1t = (kv ? P_WV1_T : P_WK1_T) + (size_t)layer * 128 * 2048;
;   const u16* w2t = (kv ? P_WV2_T : P_WK2_T) + (size_t)layer * 64 * 128;
;   const u16* src = P_H + ((size_t)b * SEQ + (size_t)(cvalid ? 16 * c : 0)) * HS + col + quad * 8;
;   const u16* wb = w1t + (size_t)l15 * 2048 + quad * 8;
;   f32x4 acc[8];
; #pragma unroll
;   for (int j = 0; j < 8; ++j) acc[j] = f32x4{0.f, 0.f, 0.f, 0.f};
; __device__ void phase_x(const Params& p, int layer, unsigned char* smem) {
;     ...
;   for (int i = blockIdx.x; i < NC; i += G) {
;     int t = i; int ct = t & 7; t >>= 3; int g = t & 1; t >>= 1; int b = t & 7; int kv = t >> 3;
;     item_compress(p, layer, kv, b, g, ct, smem);
.LBB0_232:
	s_bfe_u32 s40, s24, 0x30003
	s_and_b32 s41, s24, 7
	s_lshl_b32 s41, s41, 4
	s_or_b32 s40, s40, s41
	s_bfe_u32 s41, s24, 0x10006
	s_lshl_b32 s41, s41, 3
	s_or_b32 s40, s40, s41
	s_and_b32 s41, s24, 0x80
	s_or_b32 s29, s40, s41
	s_cmpk_gt_u32 s29, 0x7f
	s_cselect_b64 s[18:19], -1, 0
	s_lshl_b32 s41, s29, 4
	s_lshr_b32 s40, s29, 3
	s_lshr_b32 s25, s29, 4
	s_and_b32 s35, s41, 0x70
	s_cmpk_lt_u32 s29, 0x80
	s_cselect_b64 s[30:31], -1, 0
	s_bfe_u32 s29, s29, 0x30004
	v_mov_b32_e32 v73, v210
	s_and_b64 s[38:39], s[30:31], exec
	v_readlane_b32 s44, v253, 12
	v_and_b32_e32 v72, 15, v73
	s_mov_b32 s39, 0x2504400
	v_ashrrev_i32_e32 v75, 6, v73
	v_or_b32_e32 v0, s35, v72
	s_movk_i32 s38, 0x1200
	v_readlane_b32 s48, v253, 16
	v_readlane_b32 s49, v253, 17
	v_readlane_b32 s50, v253, 18
	v_readlane_b32 s51, v253, 19
	s_cselect_b32 s86, s39, 0x2704400
	s_movk_i32 s39, 0x7f
	v_lshlrev_b32_e32 v4, 12, v72
	v_mov_b32_e32 v5, v1
	v_lshlrev_b32_e32 v6, 9, v75
	s_cselect_b32 s38, s38, 0x1300
	s_cselect_b32 s42, s49, s51
	s_cselect_b32 s43, s48, s50
	v_lshlrev_b32_e32 v2, 4, v0
	v_cmp_ne_u32_e32 vcc, s39, v0
	v_lshl_add_u64 v[4:5], s[86:87], 0, v[4:5]
	v_ashrrev_i32_e32 v7, 31, v6
	s_and_b32 s39, s41, 0x80
	v_cndmask_b32_e32 v0, 0, v2, vcc
	v_lshl_add_u64 v[4:5], v[6:7], 1, v[4:5]
	s_or_b32 s38, s39, s38
	v_lshl_or_b32 v0, s29, 11, v0
	v_lshlrev_b32_e32 v8, 3, v75
	s_waitcnt vmcnt(16)
	v_lshl_add_u64 v[46:47], s[6:7], 0, v[4:5]
	v_mov_b32_e32 v4, s38
	v_mov_b32_e32 v5, v1
	v_mul_u32_u24_e32 v2, 0x1d00, v0
	v_mov_b32_e32 v3, v1
	v_mad_i64_i32 v[4:5], s[38:39], v8, s3, v[4:5]
	v_lshl_add_u64 v[2:3], v[4:5], 0, v[2:3]
	v_lshl_add_u64 v[48:49], s[88:89], 0, v[2:3]
	s_add_u32 s38, s43, s0
	v_lshlrev_b32_e32 v4, 1, v73
	v_lshlrev_b64 v[2:3], 2, v[6:7]
	s_movk_i32 s41, 0x60
	v_readlane_b32 s45, v253, 13
	s_addc_u32 s39, s42, s1
	v_and_or_b32 v2, v4, s41, v2
	v_mov_b32_e32 v6, 0
	v_lshrrev_b32_e32 v74, 4, v73
	v_and_b32_e32 v0, 48, v73
	v_lshl_add_u64 v[50:51], s[38:39], 0, v[2:3]
	s_mov_b64 s[38:39], 0
	v_mov_b32_e32 v7, v6
	v_mov_b32_e32 v8, v6
	v_mov_b32_e32 v9, v6
	v_mov_b32_e32 v10, v6
	v_mov_b32_e32 v11, v6
	v_mov_b32_e32 v12, v6
	v_mov_b32_e32 v13, v6
	v_mov_b32_e32 v14, v6
	v_mov_b32_e32 v15, v6
	v_mov_b32_e32 v16, v6
	v_mov_b32_e32 v17, v6
	v_mov_b32_e32 v18, v6
	v_mov_b32_e32 v19, v6
	v_mov_b32_e32 v20, v6
	v_mov_b32_e32 v21, v6
	v_mov_b32_e32 v22, v6
	v_mov_b32_e32 v23, v6
	v_mov_b32_e32 v24, v6
	v_mov_b32_e32 v25, v6
	v_mov_b32_e32 v26, v6
	v_mov_b32_e32 v27, v6
	v_mov_b32_e32 v28, v6
	v_mov_b32_e32 v29, v6
	v_mov_b32_e32 v30, v6
	v_mov_b32_e32 v31, v6
	v_mov_b32_e32 v32, v6
	v_mov_b32_e32 v33, v6
	v_mov_b32_e32 v2, v6
	v_mov_b32_e32 v3, v6
	v_mov_b32_e32 v4, v6
	v_mov_b32_e32 v5, v6
	s_mov_b32 s44, 0x40000
	s_mov_b32 s45, 0x60000
	v_readlane_b32 s46, v253, 14
	v_readlane_b32 s47, v253, 15
	v_readlane_b32 s52, v253, 20
	v_readlane_b32 s53, v253, 21
	v_readlane_b32 s54, v253, 22
	v_readlane_b32 s55, v253, 23
	v_readlane_b32 s56, v253, 24
	v_readlane_b32 s57, v253, 25
	v_readlane_b32 s58, v253, 26
	v_readlane_b32 s59, v253, 27

; __device__ __forceinline__ int otid() { int t = threadIdx.x; asm volatile("" : "+v"(t)); return t; }
; __device__ void item_swa(const Params& p, int layer, int b, int g, int qt, unsigned char* smem) {
;   u16* sK = (u16*)smem;
;   u16* sVt = sK + 64 * 72;
;   const int tid = otid(), lane = tid & 63, l15 = lane & 15, quad = lane >> 4;
;   const int wave = __builtin_amdgcn_readfirstlane(tid >> 6);
;   const int q0 = qt * 64;
;   const int hh = g * 2 + (wave >> 1);
;   const int qlo = q0 + (wave & 1) * 32;
;   int tq[2];
;   tq[0] = qlo + l15; tq[1] = tq[0] + 16;
;   const float slope2 = exp2f(-2.f * (float)(hh + 1)) * LOG2E;
;   const unsigned selq[2] = {0xffffffffu, 0xffffffffu};
;   const float c1 = 0.125f * LOG2E;
;   const u16* hb = P_H + (size_t)b * SEQ * HS;
;   const u16* vt = P_VT + ((size_t)b * VTC + 256 + g * 64) * SEQ;
;   bf16x8 qf[2][2];
; #pragma unroll
;   for (int n = 0; n < 2; ++n)
; #pragma unroll
;     for (int ks = 0; ks < 2; ++ks)
;       qf[n][ks] = *(const bf16x8*)(hb + (size_t)tq[n] * HS + C_QB + hh * 64 + ks * 32 + quad * 8);
;   uint2 gpre[2][4];
; #pragma unroll
;   for (int n = 0; n < 2; ++n)
; #pragma unroll
;     for (int dt = 0; dt < 4; ++dt)
;       gpre[n][dt] = *(const uint2*)(hb + (size_t)tq[n] * HS + C_GB + hh * 64 + dt * 16 + quad * 4);
;   f32x4 O[2][4];
;   float l[2] = {0.f, 0.f};
; #pragma unroll
;   for (int n = 0; n < 2; ++n)
; #pragma unroll
;     for (int dt = 0; dt < 4; ++dt) O[n][dt] = f32x4{0.f, 0.f, 0.f, 0.f};
;   int ktb = qt - 2; if (ktb < 0) ktb = 0;
;   int kte = qt + 1;
; __device__ void phase_x(const Params& p, int layer, unsigned char* smem) {
;     ...
;       int t = i; int qt = t & 31; t >>= 5; int g = t & 1; int b = t >> 1;
;       item_swa(p, layer, b, g, qt, smem);
.LBB0_242:
	v_mov_b32_e32 v0, v210
	s_bfe_u32 s19, s9, 0x50003
	v_readfirstlane_b32 s0, v0
	s_bfe_u32 s39, s9, 0x10008
	s_ashr_i32 s25, s0, 7
	s_lshr_b32 s0, s0, 1
	s_and_b32 s18, s9, 7
	s_lshl_b32 s1, s19, 6
	s_lshl_b32 s6, s39, 1
	s_and_b32 s38, s0, 32
	s_add_i32 s25, s25, s6
	s_or_b32 s35, s38, s1
	s_mul_i32 s0, s18, 0xe80000
	v_readlane_b32 s6, v254, 4
	v_and_b32_e32 v84, 15, v0
	s_mul_hi_i32 s1, s18, 0xe80000
	s_add_u32 s0, s6, s0
	v_or_b32_e32 v179, s35, v84
	s_addc_u32 s1, s33, s1
	s_lshl_b32 s6, s25, 6
	v_or_b32_e32 v178, 16, v179
	s_ashr_i32 s7, s6, 31
	v_mov_b64_e32 v[2:3], s[0:1]
	v_bfe_u32 v180, v0, 4, 2
	v_mad_u64_u32 v[4:5], s[30:31], v179, s3, v[2:3]
	s_lshl_b64 s[6:7], s[6:7], 1
	v_mad_u64_u32 v[2:3], s[30:31], v178, s3, v[2:3]
	v_lshlrev_b32_e32 v0, 3, v180
	v_lshl_add_u64 v[4:5], v[4:5], 0, s[6:7]
	v_lshlrev_b32_e32 v6, 4, v180
	v_mov_b32_e32 v7, v1
	v_lshl_add_u64 v[2:3], v[2:3], 0, s[6:7]
	v_lshl_add_u64 v[8:9], v[4:5], 0, v[6:7]
	v_lshl_add_u64 v[6:7], v[2:3], 0, v[6:7]
	v_lshl_add_u64 v[4:5], v[4:5], 0, v[0:1]
	v_lshl_add_u64 v[2:3], v[2:3], 0, v[0:1]
	global_load_dwordx4 v[32:35], v[8:9], off offset:2048
	global_load_dwordx4 v[36:39], v[8:9], off offset:2112
	global_load_dwordx4 v[40:43], v[6:7], off offset:2048
	global_load_dwordx4 v[44:47], v[6:7], off offset:2112
	global_load_dwordx2 v[170:171], v[4:5], off offset:3072
	global_load_dwordx2 v[168:169], v[4:5], off offset:3104
	global_load_dwordx2 v[166:167], v[4:5], off offset:3136
	global_load_dwordx2 v[164:165], v[4:5], off offset:3168
	global_load_dwordx2 v[162:163], v[2:3], off offset:3072
	global_load_dwordx2 v[160:161], v[2:3], off offset:3104
	global_load_dwordx2 v[158:159], v[2:3], off offset:3136
	global_load_dwordx2 v[156:157], v[2:3], off offset:3168
	s_max_u32 s40, s19, 2
	s_add_i32 s64, s19, 1
	v_sub_u32_e64 v0, s19, 2 clamp
	s_sub_i32 s29, s64, s40
	s_bitcmp0_b32 s29, 0
	v_readfirstlane_b32 s29, v0
	s_cbranch_scc1 .LBB0_248
	s_cmp_lt_u32 s19, 3
	s_mov_b64 s[30:31], -1
	s_cbranch_scc0 .LBB0_245
	s_add_i32 s41, s19, 2
	s_mov_b64 s[30:31], 0

;     ...
;   if (kt >= kt_end) { hook(); return; }
;   const bf16x8 ones = bf16x8{0x3F80, 0x3F80, 0x3F80, 0x3F80, 0x3F80, 0x3F80, 0x3F80, 0x3F80};
;   f32x4 L[NQ * NMAP];
; #pragma unroll
;   for (int i = 0; i < NQ * NMAP; ++i) L[i] = f32x4{0.f, 0.f, 0.f, 0.f};
;   int nxt = next_tile(kt);
;   {
;     u32x4 fk[TK][2], fv[TK][2];
; #pragma unroll
;     for (int t = 0; t < TK; ++t)
; #pragma unroll
;       for (int i = 0; i < 2; ++i) {
;         fk[t][i] = *(const u32x4*)(gk + (size_t)((kt + t) * 64 + i * 32) * kstride);
;         fv[t][i] = *(const u32x4*)(gv + (size_t)(i * 32) * vtstride + (kt + t) * 64);
;       }
;     if (nxt < kt_end) gload(nxt);
;     hook();
;     __syncthreads();
; #pragma unroll
;     for (int t = 0; t < TK; ++t)
; #pragma unroll
;       for (int i = 0; i < 2; ++i) {
;         *(u32x4*)(wk + t * TSZ + i * 32 * 64) = fk[t][i];
;         *(u32x4*)(wv + t * TSZ + i * 32 * 72) = fv[t][i];
;       }
;   }
;   __syncthreads();
; __device__ void item_swa(const Params& p, int layer, int b, int g, int qt, unsigned char* smem) {
;     ...
;   const int wave = __builtin_amdgcn_readfirstlane(tid >> 6);
;   const int q0 = qt * 64;
;   const int hh = g * 2 + (wave >> 1);
;   const int qlo = q0 + (wave & 1) * 32;
;   int tq[2];
;   tq[0] = qlo + l15; tq[1] = tq[0] + 16;
;   const float slope2 = exp2f(-2.f * (float)(hh + 1)) * LOG2E;
.LBB0_251:
	v_lshrrev_b32_e32 v86, 4, v85
	v_xor_b32_e32 v89, v86, v85
	v_lshlrev_b32_e32 v88, 7, v30
	v_lshlrev_b32_e32 v89, 4, v89
	s_movk_i32 s0, 0x70
	v_and_or_b32 v181, v89, s0, v88
	s_add_i32 s0, s25, 1
	v_cvt_f32_i32_e32 v89, s0
	v_lshlrev_b32_e32 v30, 4, v30
	s_bfe_u32 s0, s24, 0x50003
	v_add3_u32 v182, v88, v30, v0
	s_lshl_b32 s30, s0, 6
	v_mul_f32_e32 v0, -2.0, v89
	s_mov_b32 s0, 0xc2fc0000
	v_cmp_gt_f32_e32 vcc, s0, v0
	s_or_b32 s59, s35, 31
	s_and_b64 s[0:1], vcc, exec
	v_cndmask_b32_e32 v0, 0, v213, vcc
	v_fmac_f32_e32 v0, -2.0, v89
	v_exp_f32_e32 v0, v0
	s_cselect_b32 s0, 0xffffffc0, 0
	v_bfe_u32 v87, v85, 4, 2
	v_ldexp_f32 v0, v0, s0
	v_mul_f32_e32 v183, 0x3fb8aa3b, v0
	s_mov_b64 s[0:1], 0x20000
	v_bfe_u32 v0, v85, 1, 3
	s_barrier
	s_waitcnt vmcnt(7)
	ds_write_b128 v181, v[2:5]
	s_waitcnt vmcnt(6)
	ds_write_b128 v182, v[6:9] offset:9216
	s_waitcnt vmcnt(5)
	ds_write_b128 v181, v[10:13] offset:4096
	s_waitcnt vmcnt(4)
	ds_write_b128 v182, v[14:17] offset:13824
	s_waitcnt vmcnt(3)
	ds_write_b128 v181, v[18:21] offset:18432
	s_waitcnt vmcnt(2)
	ds_write_b128 v182, v[22:25] offset:27648
	s_waitcnt vmcnt(1)
	ds_write_b128 v181, v[26:29] offset:22528
	s_waitcnt vmcnt(0)
	ds_write_b128 v182, v[48:51] offset:32256
	v_lshl_add_u64 v[176:177], v[174:175], 0, s[0:1]
	v_bitop3_b32 v2, v86, v0, 3 bitop3:0x6c
	v_bitop3_b32 v0, v87, v0, 4 bitop3:0x36
	s_or_b32 s0, s30, s38
	v_lshlrev_b32_e32 v184, 2, v87
	v_lshlrev_b32_e32 v188, 4, v0
	v_add_u32_e32 v0, s0, v84
	v_sub_u32_e32 v0, v0, v184
	v_subrev_u32_e32 v189, s58, v0
	v_add_u32_e32 v0, s58, v184
	v_sub_u32_e32 v0, v0, v84
	v_and_b32_e32 v31, 15, v85
	v_lshlrev_b32_e32 v187, 4, v2
	v_subrev_u32_e32 v0, s38, v0
	v_mov_b32_e32 v2, v1
	v_mov_b32_e32 v3, v1
	v_lshlrev_b32_e32 v185, 7, v31
	v_mul_u32_u24_e32 v186, 0x90, v31
	v_subrev_u32_e32 v190, s30, v0
	v_mov_b32_e32 v0, v1
	v_mov_b64_e32 v[6:7], v[2:3]
	v_mov_b64_e32 v[10:11], v[2:3]
	v_mov_b64_e32 v[14:15], v[2:3]
	v_mov_b64_e32 v[18:19], v[2:3]
	v_mov_b64_e32 v[26:27], v[2:3]
	v_mov_b64_e32 v[30:31], v[2:3]
	v_mov_b64_e32 v[50:51], v[2:3]
	v_mov_b64_e32 v[86:87], v[2:3]
	v_mov_b64_e32 v[90:91], v[2:3]
	v_mov_b64_e32 v[22:23], v[2:3]
	s_mov_b32 s65, 0
	s_add_i32 s66, s35, 0xffffff80
	s_add_i32 s67, s35, 0xffffff9f
	v_mov_b64_e32 v[4:5], v[0:1]
	v_mov_b64_e32 v[8:9], v[0:1]
	v_mov_b64_e32 v[12:13], v[0:1]
	v_mov_b64_e32 v[16:17], v[0:1]
	v_mov_b64_e32 v[24:25], v[0:1]
	v_mov_b64_e32 v[28:29], v[0:1]
	v_mov_b64_e32 v[48:49], v[0:1]
	v_mov_b64_e32 v[84:85], v[0:1]
	v_mov_b64_e32 v[88:89], v[0:1]
	v_mov_b64_e32 v[20:21], v[0:1]
	s_mov_b32 s68, 0
	s_movk_i32 s74, 0x3fff
	s_movk_i32 s75, 0x210
	s_movk_i32 s76, 0xff7f
	s_mov_b32 s77, 0x40000
	s_mov_b32 s78, 0x60000
	s_waitcnt lgkmcnt(0)
	s_barrier
	v_mul_f32_e32 v219, 0x40b17218, v183
	v_mul_f32_e32 v220, 2.0, v219
	v_mul_f32_e32 v221, 0x40400000, v219
	v_mov_b32_e32 v218, 0

; __device__ __forceinline__ unsigned xb_ld(unsigned* p)              { return __hip_atomic_load(p, __ATOMIC_RELAXED, __HIP_MEMORY_SCOPE_AGENT); }
; __device__ __forceinline__ unsigned xb_add(unsigned* p, unsigned v) { return __hip_atomic_fetch_add(p, v, __ATOMIC_RELAXED, __HIP_MEMORY_SCOPE_AGENT); }
; #define XB_SPIN(cond, bar) do { unsigned _sp = 0; while (cond) { __builtin_amdgcn_s_sleep(1); \
;     if ((++_sp & 255u) == 0u) { if (xb_ld(&(bar)[XB_TMO])) break; if (_sp > XB_SPIN_CAP) { atomicAdd(&(bar)[XB_TMO], 1u); break; } } } } while (0)
; __device__ __forceinline__ void xcd_barrier(const XcdBarrier& b) {
;     asm volatile("s_waitcnt vmcnt(0)" ::: "memory");
;     __syncthreads();
;     if (threadIdx.x == 0) {
;         unsigned* bar = b.bar;
;         __builtin_amdgcn_s_waitcnt(0);
;         unsigned nloc = b.st[0], nx = b.st[1];
;         if (nloc == 0u) { xcd_barrier_complete(bar, b.x, nloc, nx); b.st[0] = nloc; b.st[1] = nx; }
;         const unsigned old = xb_add(&bar[XB_XSUB(b.x)], 1u);
;         const unsigned gen = old / nloc;
;         if (old + 1u == (gen + 1u) * nloc) {
;             __builtin_amdgcn_fence(__ATOMIC_RELEASE, "agent");
;             asm volatile("s_waitcnt vmcnt(0)" ::: "memory");
;             const unsigned og = xb_add(&bar[XB_TOP], 1u);
;             const unsigned tg = og / nx;
;             if (og + 1u == (tg + 1u) * nx) xb_add(&bar[XB_TOPGEN], 1u);
;             else XB_SPIN(xb_ld(&bar[XB_TOPGEN]) == tg, bar);
;             __builtin_amdgcn_fence(__ATOMIC_ACQUIRE, "agent");
;             xb_add(&bar[XB_XGEN(b.x)], 1u);
;             asm volatile("s_waitcnt vmcnt(0)" ::: "memory");
;         } else {
;             XB_SPIN(xb_ld(&bar[XB_XGEN(b.x)]) == gen, bar);
;             __builtin_amdgcn_fence(__ATOMIC_ACQUIRE, "agent");
;             asm volatile("s_waitcnt vmcnt(0)" ::: "memory");
;         }
;     }
;     __syncthreads();
; }
; __global__ void __launch_bounds__(256, 2) hybrid_megakernel(Params p, int ph_lo, int ph_hi) {
;     ...
;     if (ph + 1 < ph_hi) {
;       if (ph_hi > 1000) cg::this_grid().sync();
;       xcd_barrier(xb);
;     }
.Llb_have:
	s_cmp_lg_u32 s0, 1
	s_cbranch_scc1 .Llb_global
	s_lshr_b32 s1, 0x1ffffc, s52
	s_bitcmp1_b32 s1, 0
	s_cbranch_scc0 .Llb_global
	s_waitcnt vmcnt(0) lgkmcnt(0)
	s_barrier
	v_cmp_eq_u32_e32 vcc, 0, v210
	s_and_saveexec_b64 s[0:1], vcc
	s_cbranch_execz .Llbar_x
	v_readlane_b32 s6, v255, 58
	v_readlane_b32 s7, v255, 59
	v_mov_b32_e32 v0, 1
	s_nop 3
	global_atomic_add v0, v1, v0, s[6:7] sc0
	s_waitcnt vmcnt(0)
	v_readfirstlane_b32 s8, v0
	s_lshr_b32 s9, s8, 6
	s_and_b32 s8, s8, 63
	s_cmp_lg_u32 s8, 63
	s_cbranch_scc1 .Llbar_poll
	v_mov_b32_e32 v0, 1
	global_atomic_add v1, v0, s[6:7] offset:1024
	s_branch .Llbar_acq
